# compress MLP (key units): rope-table loads issued together with the token-row loads instead of after them (one round trip less per row)
# baseline (speedup 1.0000x reference)
.LBB0_302:
	s_waitcnt vmcnt(0) lgkmcnt(0)
	v_lshl_add_u64 v[58:59], v[46:47], 0, v[48:49]
	v_add_co_u32_e32 v38, vcc, 0x8b89000, v58
	v_cndmask_b32_e64 v0, 0, 1, s[10:11]
	s_nop 0
	v_addc_co_u32_e32 v39, vcc, 0, v59, vcc
	global_load_dwordx4 v[34:37], v[38:39], off offset:1024
	s_nop 0
	global_load_dwordx4 v[38:41], v[38:39], off offset:1088
	v_lshl_add_u64 v[56:57], v[46:47], 0, v[50:51]
	s_and_b64 vcc, exec, s[10:11]
	s_cbranch_vccnz .Lcmp_nocs_a
	v_add_co_u32_e32 v42, vcc, 0x2389000, v56
	s_nop 1
	v_addc_co_u32_e32 v43, vcc, 0, v57, vcc
	global_load_dwordx4 v[60:63], v[42:43], off
	global_load_dwordx4 v[64:67], v[42:43], off offset:16
	global_load_dwordx4 v[68:71], v[42:43], off offset:32
	s_nop 0
	global_load_dwordx4 v[42:45], v[42:43], off offset:48
.Lcmp_nocs_a:
	v_cmp_ne_u32_e64 s[6:7], 1, v0
	s_andn2_b64 vcc, exec, s[10:11]
	s_mov_b64 s[16:17], -1
	s_cbranch_vccnz .LBB0_304
	s_mov_b64 s[16:17], 0
.LBB0_304:
	s_andn2_b64 vcc, exec, s[16:17]
	v_lshl_add_u64 v[56:57], v[46:47], 0, v[50:51]
	s_cbranch_vccnz .LBB0_306
	s_waitcnt vmcnt(0) lgkmcnt(0)
	v_lshlrev_b32_e32 v72, 16, v38
	v_and_b32_e32 v73, 0xffff0000, v34
	v_lshlrev_b32_e32 v74, 16, v34
	v_and_b32_e32 v75, 0xffff0000, v38
	v_mov_b32_e32 v79, v73
	v_lshlrev_b32_e32 v34, 16, v35
	v_mov_b32_e32 v78, v74
	s_waitcnt vmcnt(0) lgkmcnt(0)
	v_mov_b32_e32 v76, v60
	v_mov_b32_e32 v77, v63
	v_mov_b32_e32 v54, v61
	v_mov_b32_e32 v55, v62
	v_pk_mul_f32 v[76:77], v[76:77], v[72:73]
	v_mov_b32_e32 v73, v75
	v_pk_fma_f32 v[54:55], v[54:55], v[74:75], v[76:77]
	v_mov_b32_e32 v77, v62
	v_mov_b32_e32 v62, v61
	v_mov_b32_e32 v76, v60
	v_pk_mul_f32 v[60:61], v[62:63], v[72:73]
	v_lshlrev_b32_e32 v72, 16, v39
	v_and_b32_e32 v73, 0xffff0000, v35
	v_and_b32_e32 v35, 0xffff0000, v39
	v_mov_b32_e32 v62, v64
	v_mov_b32_e32 v63, v67
	v_mov_b32_e32 v38, v65
	v_mov_b32_e32 v39, v66
	v_pk_mul_f32 v[62:63], v[62:63], v[72:73]
	v_mov_b32_e32 v75, v73
	v_mov_b32_e32 v66, v65
	v_mov_b32_e32 v73, v35
	v_pk_fma_f32 v[62:63], v[38:39], v[34:35], v[62:63]
	v_mov_b32_e32 v38, v64
	v_mov_b32_e32 v74, v34
	v_pk_mul_f32 v[34:35], v[66:67], v[72:73]
	v_mov_b32_e32 v72, v68
	v_pk_fma_f32 v[38:39], v[38:39], v[74:75], v[34:35] neg_lo:[0,0,1] neg_hi:[0,0,1]
	v_lshlrev_b32_e32 v34, 16, v40
	v_and_b32_e32 v35, 0xffff0000, v36
	v_mov_b32_e32 v73, v71
	v_lshlrev_b32_e32 v66, 16, v36
	v_and_b32_e32 v67, 0xffff0000, v40
	v_mov_b32_e32 v64, v69
	v_mov_b32_e32 v65, v70
	v_pk_mul_f32 v[72:73], v[72:73], v[34:35]
	v_mov_b32_e32 v75, v35
	v_pk_fma_f32 v[64:65], v[64:65], v[66:67], v[72:73]
	v_mov_b32_e32 v73, v70
	v_mov_b32_e32 v70, v69
	v_mov_b32_e32 v35, v67
	v_mov_b32_e32 v72, v68
	v_mov_b32_e32 v74, v66
	v_pk_mul_f32 v[34:35], v[70:71], v[34:35]
	v_lshlrev_b32_e32 v36, 16, v37
	v_pk_fma_f32 v[66:67], v[72:73], v[74:75], v[34:35] neg_lo:[0,0,1] neg_hi:[0,0,1]
	v_lshlrev_b32_e32 v34, 16, v41
	v_and_b32_e32 v35, 0xffff0000, v37
	v_and_b32_e32 v37, 0xffff0000, v41
	v_mov_b32_e32 v68, v42
	v_mov_b32_e32 v69, v45
	v_mov_b32_e32 v40, v43
	v_mov_b32_e32 v41, v44
	v_pk_mul_f32 v[68:69], v[68:69], v[34:35]
	v_mov_b32_e32 v71, v35
	v_mov_b32_e32 v44, v43
	v_mov_b32_e32 v35, v37
	v_pk_fma_f32 v[68:69], v[40:41], v[36:37], v[68:69]
	v_mov_b32_e32 v40, v42
	v_mov_b32_e32 v70, v36
	v_pk_mul_f32 v[34:35], v[44:45], v[34:35]
	v_pk_fma_f32 v[60:61], v[76:77], v[78:79], v[60:61] neg_lo:[0,0,1] neg_hi:[0,0,1]
	v_pk_fma_f32 v[40:41], v[40:41], v[70:71], v[34:35] neg_lo:[0,0,1] neg_hi:[0,0,1]
	v_cvt_pk_bf16_f32 v34, v60, v61
	v_cvt_pk_bf16_f32 v35, v38, v39
	v_cvt_pk_bf16_f32 v36, v66, v67
	v_cvt_pk_bf16_f32 v37, v40, v41
	v_cvt_pk_bf16_f32 v38, v54, v55
	v_cvt_pk_bf16_f32 v39, v62, v63
	v_cvt_pk_bf16_f32 v40, v64, v65
	v_cvt_pk_bf16_f32 v41, v68, v69
.LBB0_306:
	v_lshl_add_u64 v[54:55], v[46:47], 0, v[52:53]
	s_mov_b64 s[16:17], -1
	v_add_co_u32_e32 v144, vcc, 0x2080000, v54
	s_nop 1
	v_addc_co_u32_e32 v145, vcc, 0, v55, vcc
	global_load_dwordx4 v[146:149], v[144:145], off
	global_load_dwordx4 v[150:153], v[144:145], off offset:64
	v_add_co_u32_e32 v144, vcc, 0x2090000, v54
	s_nop 1
	v_addc_co_u32_e32 v145, vcc, 0, v55, vcc
	global_load_dwordx4 v[154:157], v[144:145], off
	global_load_dwordx4 v[158:161], v[144:145], off offset:64
	v_add_co_u32_e32 v144, vcc, 0x20a0000, v54
	s_nop 1
	v_addc_co_u32_e32 v145, vcc, 0, v55, vcc
	global_load_dwordx4 v[162:165], v[144:145], off
	global_load_dwordx4 v[166:169], v[144:145], off offset:64
	v_add_co_u32_e32 v144, vcc, 0x20b0000, v54
	s_nop 1
	v_addc_co_u32_e32 v145, vcc, 0, v55, vcc
	global_load_dwordx4 v[170:173], v[144:145], off
	global_load_dwordx4 v[174:177], v[144:145], off offset:64
	v_add_co_u32_e32 v144, vcc, 0x20c0000, v54
	s_nop 1
	v_addc_co_u32_e32 v145, vcc, 0, v55, vcc
	global_load_dwordx4 v[178:181], v[144:145], off
	global_load_dwordx4 v[182:185], v[144:145], off offset:64
	v_add_co_u32_e32 v144, vcc, 0x20d0000, v54
	s_nop 1
	v_addc_co_u32_e32 v145, vcc, 0, v55, vcc
	global_load_dwordx4 v[186:189], v[144:145], off
	global_load_dwordx4 v[190:193], v[144:145], off offset:64
	v_add_co_u32_e32 v144, vcc, 0x20e0000, v54
	s_nop 1
	v_addc_co_u32_e32 v145, vcc, 0, v55, vcc
	global_load_dwordx4 v[194:197], v[144:145], off
	global_load_dwordx4 v[200:203], v[144:145], off offset:64
	v_add_co_u32_e32 v144, vcc, 0x20f0000, v54
	s_nop 1
	v_addc_co_u32_e32 v145, vcc, 0, v55, vcc
	global_load_dwordx4 v[204:207], v[144:145], off
	global_load_dwordx4 v[208:211], v[144:145], off offset:64
	s_waitcnt vmcnt(14) lgkmcnt(0)
	v_mfma_f32_16x16x32_bf16 v[30:33], v[146:149], v[34:37], v[30:33]
	v_mfma_f32_16x16x32_bf16 v[30:33], v[150:153], v[38:41], v[30:33]
	s_waitcnt vmcnt(12)
	v_mfma_f32_16x16x32_bf16 v[26:29], v[154:157], v[34:37], v[26:29]
	v_mfma_f32_16x16x32_bf16 v[26:29], v[158:161], v[38:41], v[26:29]
	s_waitcnt vmcnt(10)
	v_mfma_f32_16x16x32_bf16 v[22:25], v[162:165], v[34:37], v[22:25]
	v_mfma_f32_16x16x32_bf16 v[22:25], v[166:169], v[38:41], v[22:25]
	s_waitcnt vmcnt(8)
	v_mfma_f32_16x16x32_bf16 v[18:21], v[170:173], v[34:37], v[18:21]
	v_mfma_f32_16x16x32_bf16 v[18:21], v[174:177], v[38:41], v[18:21]
	s_waitcnt vmcnt(6)
	v_mfma_f32_16x16x32_bf16 v[14:17], v[178:181], v[34:37], v[14:17]
	v_mfma_f32_16x16x32_bf16 v[14:17], v[182:185], v[38:41], v[14:17]
	s_waitcnt vmcnt(4)
	v_mfma_f32_16x16x32_bf16 v[10:13], v[186:189], v[34:37], v[10:13]
	v_mfma_f32_16x16x32_bf16 v[10:13], v[190:193], v[38:41], v[10:13]
	s_waitcnt vmcnt(2)
	v_mfma_f32_16x16x32_bf16 v[6:9], v[194:197], v[34:37], v[6:9]
	v_mfma_f32_16x16x32_bf16 v[6:9], v[200:203], v[38:41], v[6:9]
	s_waitcnt vmcnt(0)
	v_mfma_f32_16x16x32_bf16 v[2:5], v[204:207], v[34:37], v[2:5]
	v_mfma_f32_16x16x32_bf16 v[2:5], v[208:211], v[38:41], v[2:5]
	v_add_co_u32_e32 v38, vcc, 0x8b8a000, v58
	s_nop 1
	v_addc_co_u32_e32 v39, vcc, 0, v59, vcc
	global_load_dwordx4 v[34:37], v[38:39], off offset:2048
	s_nop 0
	global_load_dwordx4 v[38:41], v[38:39], off offset:2112
	s_and_b64 vcc, exec, s[10:11]
	s_cbranch_vccnz .Lcmp_nocs_b
	v_add_co_u32_e32 v42, vcc, 0x2389000, v56
	s_nop 1
	v_addc_co_u32_e32 v43, vcc, 0, v57, vcc
	global_load_dwordx4 v[58:61], v[42:43], off offset:256
	global_load_dwordx4 v[62:65], v[42:43], off offset:272
	global_load_dwordx4 v[66:69], v[42:43], off offset:288
	s_nop 0
	global_load_dwordx4 v[42:45], v[42:43], off offset:304
.Lcmp_nocs_b:
	s_and_b64 vcc, exec, s[6:7]
	s_cbranch_vccnz .LBB0_308
	s_mov_b64 s[16:17], 0
.LBB0_308:
	s_andn2_b64 vcc, exec, s[16:17]
	s_cbranch_vccnz .LBB0_301
	s_waitcnt vmcnt(0) lgkmcnt(0)
	v_lshlrev_b32_e32 v70, 16, v38
	v_and_b32_e32 v71, 0xffff0000, v34
	v_lshlrev_b32_e32 v72, 16, v34
	v_and_b32_e32 v73, 0xffff0000, v38
	v_mov_b32_e32 v77, v71
	v_lshlrev_b32_e32 v34, 16, v35
	v_mov_b32_e32 v76, v72
	s_waitcnt vmcnt(0) lgkmcnt(0)
	v_mov_b32_e32 v74, v58
	v_mov_b32_e32 v75, v61
	v_mov_b32_e32 v56, v59
	v_mov_b32_e32 v57, v60
	v_pk_mul_f32 v[74:75], v[74:75], v[70:71]
	v_mov_b32_e32 v71, v73
	v_pk_fma_f32 v[56:57], v[56:57], v[72:73], v[74:75]
	v_mov_b32_e32 v75, v60
	v_mov_b32_e32 v60, v59
	v_mov_b32_e32 v74, v58
	v_pk_mul_f32 v[58:59], v[60:61], v[70:71]
	v_lshlrev_b32_e32 v70, 16, v39
	v_and_b32_e32 v71, 0xffff0000, v35
	v_and_b32_e32 v35, 0xffff0000, v39
	v_mov_b32_e32 v60, v62
	v_mov_b32_e32 v61, v65
	v_mov_b32_e32 v38, v63
	v_mov_b32_e32 v39, v64
	v_pk_mul_f32 v[60:61], v[60:61], v[70:71]
	v_mov_b32_e32 v73, v71
	v_mov_b32_e32 v64, v63
	v_mov_b32_e32 v71, v35
	v_pk_fma_f32 v[60:61], v[38:39], v[34:35], v[60:61]
	v_mov_b32_e32 v38, v62
	v_mov_b32_e32 v72, v34
	v_pk_mul_f32 v[34:35], v[64:65], v[70:71]
	v_mov_b32_e32 v70, v66
	v_pk_fma_f32 v[38:39], v[38:39], v[72:73], v[34:35] neg_lo:[0,0,1] neg_hi:[0,0,1]
	v_lshlrev_b32_e32 v34, 16, v40
	v_and_b32_e32 v35, 0xffff0000, v36
	v_mov_b32_e32 v71, v69
	v_lshlrev_b32_e32 v64, 16, v36
	v_and_b32_e32 v65, 0xffff0000, v40
	v_mov_b32_e32 v62, v67
	v_mov_b32_e32 v63, v68
	v_pk_mul_f32 v[70:71], v[70:71], v[34:35]
	v_mov_b32_e32 v73, v35
	v_pk_fma_f32 v[62:63], v[62:63], v[64:65], v[70:71]
	v_mov_b32_e32 v71, v68
	v_mov_b32_e32 v68, v67
	v_mov_b32_e32 v35, v65
	v_mov_b32_e32 v70, v66
	v_mov_b32_e32 v72, v64
	v_pk_mul_f32 v[34:35], v[68:69], v[34:35]
	v_lshlrev_b32_e32 v36, 16, v37
	v_pk_fma_f32 v[64:65], v[70:71], v[72:73], v[34:35] neg_lo:[0,0,1] neg_hi:[0,0,1]
	v_lshlrev_b32_e32 v34, 16, v41
	v_and_b32_e32 v35, 0xffff0000, v37
	v_and_b32_e32 v37, 0xffff0000, v41
	v_mov_b32_e32 v66, v42
	v_mov_b32_e32 v67, v45
	v_mov_b32_e32 v40, v43
	v_mov_b32_e32 v41, v44
	v_pk_mul_f32 v[66:67], v[66:67], v[34:35]
	v_mov_b32_e32 v69, v35
	v_mov_b32_e32 v44, v43
	v_mov_b32_e32 v35, v37
	v_pk_fma_f32 v[66:67], v[40:41], v[36:37], v[66:67]
	v_mov_b32_e32 v40, v42
	v_mov_b32_e32 v68, v36
	v_pk_mul_f32 v[34:35], v[44:45], v[34:35]
	v_pk_fma_f32 v[58:59], v[74:75], v[76:77], v[58:59] neg_lo:[0,0,1] neg_hi:[0,0,1]
	v_pk_fma_f32 v[40:41], v[40:41], v[68:69], v[34:35] neg_lo:[0,0,1] neg_hi:[0,0,1]
	v_cvt_pk_bf16_f32 v34, v58, v59
	v_cvt_pk_bf16_f32 v35, v38, v39
	v_cvt_pk_bf16_f32 v36, v64, v65
	v_cvt_pk_bf16_f32 v37, v40, v41
	v_cvt_pk_bf16_f32 v38, v56, v57
	v_cvt_pk_bf16_f32 v39, v60, v61
	v_cvt_pk_bf16_f32 v40, v62, v63
	v_cvt_pk_bf16_f32 v41, v66, v67
	s_branch .LBB0_301
